# v32 + LayerNorm row loops: L2 touch of the row two ahead (one dword per 64 B) so the next row's register prefetch hits L2
# baseline (speedup 1.0000x reference)
; DI void ln_phase(float* io, bf16* act, const float* w, const float* b, const bool wr_f32, const bool wr_bf16) {
;     ...
;     if (gw < T) { const f32x4* x0 = (const f32x4*)(io + (size_t)gw * D) + lane;
; #pragma unroll
;         for (int j = 0; j < 4; ++j) nv[j] = x0[64 * j]; }
;     for (int r = gw; r < T; r += ngw) {
;         f32x4* xr = (f32x4*)(io + (size_t)r * D) + lane; f32x4 v[4]; float s = 0.f;
; #pragma unroll
;         for (int j = 0; j < 4; ++j) { v[j] = nv[j]; s += (v[j][0] + v[j][1]) + (v[j][2] + v[j][3]); }
;         if (r + ngw < T) { const f32x4* xn = (const f32x4*)(io + (size_t)(r + ngw) * D) + lane;
; #pragma unroll
;             for (int j = 0; j < 4; ++j) nv[j] = xn[64 * j]; }
;         const float mean = wave_sum(s) * (1.f / D); float s2 = 0.f;
; #pragma unroll
;         for (int j = 0; j < 4; ++j) { v[j] = v[j] - mean; s2 += (v[j][0] * v[j][0] + v[j][1] * v[j][1]) + (v[j][2] * v[j][2] + v[j][3] * v[j][3]); }
;         const float rstd = 1.f / sqrtf(wave_sum(s2) * (1.f / D) + LN_EPS);
.LBB0_1110:
	s_or_b64 exec, exec, s[0:1]
	v_readlane_b32 s6, v252, 0
	v_readlane_b32 s7, v252, 1
	v_readlane_b32 s0, v254, 35
	s_waitcnt lgkmcnt(0)
	v_mov_b32_e32 v0, v232
	s_barrier
	s_lshl_b32 s90, s0, 10
	v_readlane_b32 s0, v252, 2
	v_ashrrev_i32_e32 v16, 6, v0
	v_readlane_b32 s1, v254, 36
	v_add_u32_e32 v32, s0, v16
	s_mov_b32 s0, 0x8000
	v_cmp_gt_i32_e32 vcc, s0, v32
	s_and_saveexec_b64 s[4:5], vcc
	s_cbranch_execz .LBB0_1115
	s_load_dwordx4 s[0:3], s[6:7], 0x118
	s_load_dwordx4 s[8:11], s[6:7], 0xe0
	v_ashrrev_i32_e32 v33, 31, v32
	v_and_b32_e32 v18, 63, v0
	v_lshlrev_b64 v[0:1], 12, v[32:33]
	v_lshlrev_b32_e32 v192, 4, v18
	s_waitcnt lgkmcnt(0)
	v_lshl_add_u64 v[0:1], s[0:1], 0, v[0:1]
	v_lshl_add_u64 v[0:1], v[0:1], 0, v[192:193]
	global_load_dwordx4 v[12:15], v[0:1], off
	global_load_dwordx4 v[8:11], v[0:1], off offset:1024
	global_load_dwordx4 v[4:7], v[0:1], off offset:2048
	s_nop 0
	global_load_dwordx4 v[0:3], v[0:1], off offset:3072
	v_and_b32_e32 v17, 64, v238
	v_add_u32_e32 v17, 64, v17
	v_xor_b32_e32 v19, 1, v238
	v_cmp_lt_i32_e32 vcc, v19, v17
	s_lshl_b64 s[6:7], s[90:91], 2
	s_add_u32 s10, s10, s6
	v_cndmask_b32_e32 v19, v238, v19, vcc
	v_lshlrev_b32_e32 v43, 2, v19
	v_xor_b32_e32 v19, 2, v238
	v_cmp_lt_i32_e32 vcc, v19, v17
	s_addc_u32 s11, s11, s7
	s_add_u32 s6, s8, s6
	v_cndmask_b32_e32 v19, v238, v19, vcc
	v_lshlrev_b32_e32 v44, 2, v19
	v_xor_b32_e32 v19, 4, v238
	v_cmp_lt_i32_e32 vcc, v19, v17
	s_addc_u32 s7, s9, s7
	v_lshl_add_u64 v[34:35], s[6:7], 0, v[192:193]
	v_cndmask_b32_e32 v19, v238, v19, vcc
	v_lshlrev_b32_e32 v45, 2, v19
	v_xor_b32_e32 v19, 8, v238
	v_cmp_lt_i32_e32 vcc, v19, v17
	v_readlane_b32 s6, v254, 3
	v_lshl_add_u64 v[36:37], s[10:11], 0, v[192:193]
	v_cndmask_b32_e32 v19, v238, v19, vcc
	v_lshlrev_b32_e32 v46, 2, v19
	v_xor_b32_e32 v19, 16, v238
	v_cmp_lt_i32_e32 vcc, v19, v17
	v_add_u32_e32 v16, s6, v16
	s_nop 0
	v_cndmask_b32_e32 v19, v238, v19, vcc
	v_lshlrev_b32_e32 v47, 2, v19
	v_xor_b32_e32 v19, 32, v238
	v_cmp_lt_i32_e32 vcc, v19, v17
	s_nop 1
	v_cndmask_b32_e32 v17, v238, v19, vcc
	v_lshlrev_b32_e32 v48, 2, v17
	v_ashrrev_i32_e32 v17, 31, v16
	v_lshlrev_b64 v[16:17], 12, v[16:17]
	v_or_b32_e32 v16, v16, v192
	v_lshl_add_u64 v[38:39], s[0:1], 0, v[16:17]
	v_lshlrev_b64 v[16:17], 11, v[32:33]
	v_lshl_or_b32 v16, v18, 3, v16
	v_lshl_add_u64 v[16:17], s[2:3], 0, v[16:17]
	s_mov_b64 s[0:1], 0x4000600
	v_lshl_add_u64 v[40:41], v[16:17], 0, s[0:1]
	s_mov_b64 s[2:3], 0
	global_load_dwordx4 v[64:67], v[34:35], off
	global_load_dwordx4 v[68:71], v[36:37], off
	global_load_dwordx4 v[72:75], v[34:35], off offset:1024
	global_load_dwordx4 v[76:79], v[36:37], off offset:1024
	global_load_dwordx4 v[80:83], v[34:35], off offset:2048
	global_load_dwordx4 v[84:87], v[36:37], off offset:2048
	global_load_dwordx4 v[88:91], v[34:35], off offset:3072
	global_load_dwordx4 v[92:95], v[36:37], off offset:3072
	s_waitcnt vmcnt(0)
	v_readlane_b32 s100, v254, 15
	v_readlane_b32 s101, v254, 16
	v_mul_u32_u24_e32 v102, 48, v238
	v_mov_b32_e32 v103, 0
	s_nop 0
	v_lshl_add_u64 v[100:101], v[102:103], 0, s[100:101]
	s_branch .LBB0_1113
.LBB0_1112:
	s_or_b64 exec, exec, s[6:7]
	v_add_f32_e32 v33, v12, v13
	v_add_f32_e32 v42, v14, v15
	v_add_f32_e32 v33, v33, v42
	v_add_f32_e32 v42, v8, v9
	v_add_f32_e32 v49, v10, v11
	v_add_f32_e32 v33, 0, v33
	v_add_f32_e32 v42, v42, v49
	v_add_f32_e32 v33, v42, v33
	v_add_f32_e32 v42, v4, v5
	v_add_f32_e32 v49, v6, v7
	v_add_f32_e32 v42, v42, v49
	v_add_f32_e32 v33, v42, v33
	v_add_f32_e32 v42, v0, v1
	v_add_f32_e32 v49, v2, v3
	v_add_f32_e32 v42, v42, v49
	v_add_f32_e32 v33, v42, v33
	s_and_b64 s[0:1], exec, vcc
	s_or_b64 s[2:3], s[0:1], s[2:3]
	s_mov_b32 s0, 0xf800000
	s_nop 1
	v_add_f32_dpp v33, v33, v33 quad_perm:[1,0,3,2] row_mask:0xf bank_mask:0xf
	s_nop 1
	v_add_f32_dpp v33, v33, v33 quad_perm:[2,3,0,1] row_mask:0xf bank_mask:0xf
	s_nop 1
	v_add_f32_dpp v33, v33, v33 row_half_mirror row_mask:0xf bank_mask:0xf
	s_nop 1
	v_add_f32_dpp v33, v33, v33 row_mirror row_mask:0xf bank_mask:0xf
	s_nop 1
	v_add_f32_dpp v33, v33, v33 row_bcast:15 row_mask:0xa bank_mask:0xf
	s_nop 1
	v_add_f32_dpp v33, v33, v33 row_bcast:31 row_mask:0xc bank_mask:0xf
	s_nop 1
	v_readlane_b32 s98, v33, 63
	s_nop 1
	v_mov_b32_e32 v33, s98
	v_fmac_f32_e32 v13, 0xba800000, v33
	v_fmac_f32_e32 v12, 0xba800000, v33
	v_fmac_f32_e32 v15, 0xba800000, v33
	v_fmac_f32_e32 v14, 0xba800000, v33
	v_pk_mul_f32 v[50:51], v[14:15], v[14:15]
	v_pk_mul_f32 v[52:53], v[12:13], v[12:13]
	v_fmac_f32_e32 v9, 0xba800000, v33
	v_pk_mov_b32 v[54:55], v[52:53], v[50:51] op_sel:[1,0]
	v_mov_b32_e32 v53, v51
	v_fmac_f32_e32 v8, 0xba800000, v33
	v_fmac_f32_e32 v11, 0xba800000, v33
	v_fmac_f32_e32 v10, 0xba800000, v33
	v_pk_add_f32 v[50:51], v[54:55], v[52:53]
	v_pk_mul_f32 v[52:53], v[10:11], v[10:11]
	v_pk_mul_f32 v[54:55], v[8:9], v[8:9]
	v_fmac_f32_e32 v4, 0xba800000, v33
	v_pk_mov_b32 v[56:57], v[54:55], v[52:53] op_sel:[1,0]
	v_mov_b32_e32 v55, v53
	v_fmac_f32_e32 v6, 0xba800000, v33
	v_fmac_f32_e32 v5, 0xba800000, v33
	v_mul_f32_e32 v42, v4, v4
	v_pk_add_f32 v[52:53], v[56:57], v[54:55]
	v_fmac_f32_e32 v7, 0xba800000, v33
	v_pk_fma_f32 v[54:55], v[4:5], v[4:5], v[42:43] op_sel_hi:[1,1,0]
	v_mul_f32_e32 v42, v6, v6
	v_pk_add_f32 v[50:51], v[50:51], v[50:51] op_sel_hi:[0,1]
; DI unsigned pk2(float lo, float hi) { const f32x2 v = {lo, hi}; const bf16x2_t b = __builtin_convertvector(v, bf16x2_t); return __builtin_bit_cast(unsigned, b); }
; DI void ln_phase(float* io, bf16* act, const float* w, const float* b, const bool wr_f32, const bool wr_bf16) {
;     ...
;         if (r + ngw < T) { const f32x4* xn = (const f32x4*)(io + (size_t)(r + ngw) * D) + lane;
; #pragma unroll
;             for (int j = 0; j < 4; ++j) nv[j] = xn[64 * j]; }
;     ...
;         const float rstd = 1.f / sqrtf(wave_sum(s2) * (1.f / D) + LN_EPS);
;         v2u* o8 = (v2u*)(act + (size_t)r * D) + lane;
; #pragma unroll
;         for (int j = 0; j < 4; ++j) { const f32x4 wv = ((const f32x4*)w)[lane + 64 * j], bv = ((const f32x4*)b)[lane + 64 * j];
;             f32x4 y; y[0] = v[j][0] * rstd * wv[0] + bv[0]; y[1] = v[j][1] * rstd * wv[1] + bv[1]; y[2] = v[j][2] * rstd * wv[2] + bv[2]; y[3] = v[j][3] * rstd * wv[3] + bv[3];
;             if (wr_f32) xr[64 * j] = y; if (wr_bf16) { v2u p; p.x = pk2(y[0], y[1]); p.y = pk2(y[2], y[3]); o8[64 * j] = p; } }
	v_pk_add_f32 v[52:53], v[52:53], v[52:53] op_sel_hi:[0,1]
	v_pk_fma_f32 v[56:57], v[6:7], v[6:7], v[42:43] op_sel_hi:[1,1,0]
	v_fmac_f32_e32 v3, 0xba800000, v33
	v_fmac_f32_e32 v2, 0xba800000, v33
	v_fmac_f32_e32 v1, 0xba800000, v33
	v_fmac_f32_e32 v0, 0xba800000, v33
	v_mul_f32_e32 v54, v0, v0
	v_mul_f32_e32 v56, v1, v1
	v_mul_f32_e32 v50, v2, v2
	v_mul_f32_e32 v52, v3, v3
	v_pk_add_f32 v[54:55], v[54:55], v[56:57]
	v_pk_add_f32 v[50:51], v[50:51], v[52:53]
	s_nop 0
	v_pk_add_f32 v[50:51], v[54:55], v[50:51]
	s_nop 0
	v_add_f32_e32 v33, v50, v51
	s_nop 1
	v_add_f32_dpp v33, v33, v33 quad_perm:[1,0,3,2] row_mask:0xf bank_mask:0xf
	s_nop 1
	v_add_f32_dpp v33, v33, v33 quad_perm:[2,3,0,1] row_mask:0xf bank_mask:0xf
	s_nop 1
	v_add_f32_dpp v33, v33, v33 row_half_mirror row_mask:0xf bank_mask:0xf
	s_nop 1
	v_add_f32_dpp v33, v33, v33 row_mirror row_mask:0xf bank_mask:0xf
	s_nop 1
	v_add_f32_dpp v33, v33, v33 row_bcast:15 row_mask:0xa bank_mask:0xf
	s_nop 1
	v_add_f32_dpp v33, v33, v33 row_bcast:31 row_mask:0xc bank_mask:0xf
	s_nop 1
	v_readlane_b32 s98, v33, 63
	s_nop 1
	v_mov_b32_e32 v33, s98
	v_fmamk_f32 v33, v33, 0x3a800000, v235
	v_cmp_gt_f32_e32 vcc, s0, v33
	v_mul_f32_e32 v42, 0x4f800000, v33
	s_nop 0
	v_cndmask_b32_e32 v33, v33, v42, vcc
	v_sqrt_f32_e32 v42, v33
	s_nop 0
	v_add_u32_e32 v49, -1, v42
	v_fma_f32 v50, -v49, v42, v33
	v_cmp_ge_f32_e64 s[0:1], 0, v50
	v_add_u32_e32 v50, 1, v42
	s_nop 0
	v_cndmask_b32_e64 v49, v42, v49, s[0:1]
	v_fma_f32 v42, -v50, v42, v33
	v_cmp_lt_f32_e64 s[0:1], 0, v42
	s_nop 1
	v_cndmask_b32_e64 v42, v49, v50, s[0:1]
	v_mul_f32_e32 v49, 0x37800000, v42
	v_cndmask_b32_e32 v42, v42, v49, vcc
	v_cmp_class_f32_e32 vcc, v33, v234
	s_nop 1
	v_cndmask_b32_e32 v33, v42, v33, vcc
	v_div_scale_f32 v42, s[0:1], v33, v33, 1.0
	v_rcp_f32_e32 v49, v42
	v_readlane_b32 s0, v254, 15
	v_readlane_b32 s1, v254, 16
	v_fma_f32 v50, -v42, v49, 1.0
	v_fmac_f32_e32 v49, v50, v49
	v_div_scale_f32 v50, vcc, 1.0, v33, 1.0
	v_mul_f32_e32 v51, v50, v49
	v_fma_f32 v52, -v42, v51, v50
	v_fmac_f32_e32 v51, v52, v49
	v_fma_f32 v42, -v42, v51, v50
	v_div_fmas_f32 v42, v42, v49, v51
	v_div_fixup_f32 v42, v42, v33, 1.0
	v_pk_mul_f32 v[12:13], v[12:13], v[42:43] op_sel_hi:[1,0]
	v_pk_mul_f32 v[14:15], v[14:15], v[42:43] op_sel_hi:[1,0]
	v_pk_mul_f32 v[8:9], v[8:9], v[42:43] op_sel_hi:[1,0]
	v_pk_mul_f32 v[10:11], v[10:11], v[42:43] op_sel_hi:[1,0]
	v_pk_mul_f32 v[4:5], v[4:5], v[42:43] op_sel_hi:[1,0]
	v_pk_mul_f32 v[6:7], v[6:7], v[42:43] op_sel_hi:[1,0]
	v_pk_mul_f32 v[0:1], v[0:1], v[42:43] op_sel_hi:[1,0]
	v_pk_mul_f32 v[2:3], v[2:3], v[42:43] op_sel_hi:[1,0]
	v_lshl_add_u64 v[38:39], v[38:39], 0, s[0:1]
	v_readlane_b32 s0, v254, 17
	v_readlane_b32 s1, v254, 18
	v_pk_fma_f32 v[12:13], v[64:65], v[12:13], v[68:69]
	v_pk_fma_f32 v[14:15], v[66:67], v[14:15], v[70:71]
	v_cvt_pk_bf16_f32 v12, v12, v13
	v_cvt_pk_bf16_f32 v13, v14, v15
	global_store_dwordx2 v[40:41], v[12:13], off offset:-1536
	s_nop 0
	v_pk_fma_f32 v[8:9], v[72:73], v[8:9], v[76:77]
	v_pk_fma_f32 v[10:11], v[74:75], v[10:11], v[78:79]
	v_cvt_pk_bf16_f32 v8, v8, v9
	v_cvt_pk_bf16_f32 v9, v10, v11
	global_store_dwordx2 v[40:41], v[8:9], off offset:-1024
	s_nop 0
	v_pk_fma_f32 v[4:5], v[80:81], v[4:5], v[84:85]
	v_pk_fma_f32 v[6:7], v[82:83], v[6:7], v[86:87]
	v_cvt_pk_bf16_f32 v4, v4, v5
	v_cvt_pk_bf16_f32 v5, v6, v7
	global_store_dwordx2 v[40:41], v[4:5], off offset:-512
	s_nop 0
	s_waitcnt vmcnt(4)
	v_mov_b32_e32 v12, v20
	v_mov_b32_e32 v13, v21
	v_mov_b32_e32 v14, v22
	v_mov_b32_e32 v15, v23
	v_pk_fma_f32 v[0:1], v[88:89], v[0:1], v[92:93]
	v_pk_fma_f32 v[2:3], v[90:91], v[2:3], v[94:95]
	v_cvt_pk_bf16_f32 v0, v0, v1
	v_cvt_pk_bf16_f32 v1, v2, v3
	global_store_dwordx2 v[40:41], v[0:1], off
	v_lshl_add_u64 v[40:41], v[40:41], 0, s[0:1]
	v_mov_b32_e32 v8, v24
	v_mov_b32_e32 v9, v25
	v_mov_b32_e32 v10, v26
	v_mov_b32_e32 v11, v27
	v_mov_b32_e32 v4, v28
	v_mov_b32_e32 v5, v29
	v_mov_b32_e32 v6, v30
	v_mov_b32_e32 v7, v31
	v_mov_b32_e32 v0, v16
	v_mov_b32_e32 v1, v17
	v_mov_b32_e32 v2, v18
	v_mov_b32_e32 v3, v19
	s_andn2_b64 exec, exec, s[2:3]
	s_cbranch_execz .LBB0_1115
.LBB0_1113:
	v_add_u32_e32 v32, s78, v32
	s_mov_b32 s0, 0x8000
	s_movk_i32 s6, 0x7fff
	v_cmp_gt_i32_e64 s[0:1], s0, v32
	v_cmp_lt_i32_e32 vcc, s6, v32
	v_mov_b32_e32 v20, v12
	v_mov_b32_e32 v21, v13
	v_mov_b32_e32 v22, v14
	v_mov_b32_e32 v23, v15
	v_mov_b32_e32 v24, v8
	v_mov_b32_e32 v25, v9
	v_mov_b32_e32 v26, v10
	v_mov_b32_e32 v27, v11
	v_mov_b32_e32 v28, v4
	v_mov_b32_e32 v29, v5
	v_mov_b32_e32 v30, v6
	v_mov_b32_e32 v31, v7
	v_mov_b32_e32 v16, v0
	v_mov_b32_e32 v17, v1
	v_mov_b32_e32 v18, v2
	v_mov_b32_e32 v19, v3
	s_and_saveexec_b64 s[6:7], s[0:1]
	s_cbranch_execz .LBB0_1112
	global_load_dwordx4 v[20:23], v[38:39], off
	global_load_dwordx4 v[24:27], v[38:39], off offset:1024
	global_load_dwordx4 v[28:31], v[38:39], off offset:2048
	global_load_dwordx4 v[16:19], v[38:39], off offset:3072
	v_readfirstlane_b32 s99, v32
	s_add_i32 s99, s99, s78
	s_cmp_lt_i32 s99, 0x8000
	s_cbranch_scc0 .Lln1_pf0
	v_lshl_add_u64 v[98:99], v[38:39], 0, v[100:101]
	s_branch .Lln1_pf1
.Lln1_pf0:
	v_lshl_add_u64 v[98:99], v[38:39], 0, v[102:103]
.Lln1_pf1:
	global_load_dword v96, v[98:99], off
	s_branch .LBB0_1112

; DI void ln_phase(float* io, bf16* act, const float* w, const float* b, const bool wr_f32, const bool wr_bf16) {
;     ...
;     if (gw < T) { const f32x4* x0 = (const f32x4*)(io + (size_t)gw * D) + lane;
; #pragma unroll
;         for (int j = 0; j < 4; ++j) nv[j] = x0[64 * j]; }
;     for (int r = gw; r < T; r += ngw) {
;         f32x4* xr = (f32x4*)(io + (size_t)r * D) + lane; f32x4 v[4]; float s = 0.f;
; #pragma unroll
;         for (int j = 0; j < 4; ++j) { v[j] = nv[j]; s += (v[j][0] + v[j][1]) + (v[j][2] + v[j][3]); }
;         if (r + ngw < T) { const f32x4* xn = (const f32x4*)(io + (size_t)(r + ngw) * D) + lane;
; #pragma unroll
;             for (int j = 0; j < 4; ++j) nv[j] = xn[64 * j]; }
.LBB0_1311:
	s_or_b64 exec, exec, s[0:1]
	v_readlane_b32 s10, v252, 0
	v_readlane_b32 s11, v252, 1
	s_waitcnt lgkmcnt(0)
	v_mov_b32_e32 v0, v232
	s_barrier
	v_readlane_b32 s0, v252, 2
	v_ashrrev_i32_e32 v12, 6, v0
	s_nop 0
	v_add_u32_e32 v32, s0, v12
	s_mov_b32 s0, 0x8000
	v_cmp_gt_i32_e32 vcc, s0, v32
	s_and_saveexec_b64 s[8:9], vcc
	s_cbranch_execz .LBB0_1324
	s_load_dwordx8 s[0:7], s[10:11], 0x108
	v_ashrrev_i32_e32 v33, 31, v32
	v_and_b32_e32 v14, 63, v0
	v_lshlrev_b64 v[0:1], 12, v[32:33]
	v_lshlrev_b32_e32 v192, 4, v14
	s_waitcnt lgkmcnt(0)
	v_lshl_add_u64 v[34:35], s[4:5], 0, v[0:1]
	v_lshl_add_u64 v[0:1], v[34:35], 0, v[192:193]
	global_load_dwordx4 v[28:31], v[0:1], off
	global_load_dwordx4 v[8:11], v[0:1], off offset:1024
	global_load_dwordx4 v[4:7], v[0:1], off offset:2048
	s_nop 0
	global_load_dwordx4 v[0:3], v[0:1], off offset:3072
	v_and_b32_e32 v13, 64, v238
	v_add_u32_e32 v13, 64, v13
	v_xor_b32_e32 v15, 1, v238
	v_cmp_lt_i32_e32 vcc, v15, v13
	s_lshl_b64 s[10:11], s[90:91], 2
	s_add_u32 s2, s2, s10
	v_cndmask_b32_e32 v15, v238, v15, vcc
	v_lshlrev_b32_e32 v48, 2, v15
	v_xor_b32_e32 v15, 2, v238
	v_cmp_lt_i32_e32 vcc, v15, v13
	s_addc_u32 s3, s3, s11
	s_add_u32 s0, s0, s10
	v_cndmask_b32_e32 v15, v238, v15, vcc
	v_lshlrev_b32_e32 v49, 2, v15
	v_xor_b32_e32 v15, 4, v238
	v_cmp_lt_i32_e32 vcc, v15, v13
	s_addc_u32 s1, s1, s11
	v_lshl_add_u64 v[36:37], s[0:1], 0, v[192:193]
	v_cndmask_b32_e32 v15, v238, v15, vcc
	v_lshlrev_b32_e32 v50, 2, v15
	v_xor_b32_e32 v15, 8, v238
	v_cmp_lt_i32_e32 vcc, v15, v13
	v_readlane_b32 s0, v254, 3
	v_lshl_add_u64 v[38:39], s[2:3], 0, v[192:193]
	v_cndmask_b32_e32 v15, v238, v15, vcc
	v_lshlrev_b32_e32 v51, 2, v15
	v_xor_b32_e32 v15, 16, v238
	v_cmp_lt_i32_e32 vcc, v15, v13
	v_add_u32_e32 v12, s0, v12
	s_mov_b64 s[0:1], 0x4000000
	v_cndmask_b32_e32 v15, v238, v15, vcc
	v_lshlrev_b32_e32 v52, 2, v15
	v_xor_b32_e32 v15, 32, v238
	v_cmp_lt_i32_e32 vcc, v15, v13
	s_nop 1
	v_cndmask_b32_e32 v13, v238, v15, vcc
	v_lshlrev_b32_e32 v53, 2, v13
	v_ashrrev_i32_e32 v13, 31, v12
	v_lshlrev_b64 v[12:13], 12, v[12:13]
	v_lshl_add_u64 v[40:41], s[4:5], 0, v[12:13]
	v_lshlrev_b64 v[12:13], 11, v[32:33]
	v_lshl_or_b32 v12, v14, 3, v12
	v_lshl_add_u64 v[12:13], s[6:7], 0, v[12:13]
	v_lshl_add_u64 v[42:43], v[12:13], 0, s[0:1]
	s_mov_b64 s[4:5], 0
	global_load_dwordx4 v[64:67], v[36:37], off
	global_load_dwordx4 v[68:71], v[38:39], off
	global_load_dwordx4 v[72:75], v[36:37], off offset:1024
	global_load_dwordx4 v[76:79], v[38:39], off offset:1024
	global_load_dwordx4 v[80:83], v[36:37], off offset:2048
	global_load_dwordx4 v[84:87], v[38:39], off offset:2048
	global_load_dwordx4 v[88:91], v[36:37], off offset:3072
	global_load_dwordx4 v[92:95], v[38:39], off offset:3072
	s_waitcnt vmcnt(0)
	v_readlane_b32 s100, v254, 15
	v_readlane_b32 s101, v254, 16
	v_mul_u32_u24_e32 v102, 64, v238
	v_mov_b32_e32 v103, 0
	s_nop 0
	v_lshl_add_u64 v[100:101], v[102:103], 0, s[100:101]
	s_branch .LBB0_1314
.LBB0_1313:
	s_and_b64 s[0:1], exec, s[0:1]
	s_or_b64 s[4:5], s[0:1], s[4:5]
	v_readlane_b32 s0, v254, 15
	v_readlane_b32 s2, v254, 17
	v_readlane_b32 s1, v254, 16
	v_readlane_b32 s3, v254, 18
	s_waitcnt vmcnt(5)
	v_mov_b32_e32 v28, v12
	v_lshl_add_u64 v[40:41], v[40:41], 0, s[0:1]
	v_lshl_add_u64 v[42:43], v[42:43], 0, s[2:3]
	v_lshl_add_u64 v[34:35], v[34:35], 0, s[0:1]
	v_mov_b32_e32 v29, v13
	v_mov_b32_e32 v30, v14
	v_mov_b32_e32 v31, v15
	v_mov_b32_e32 v8, v16
	v_mov_b32_e32 v9, v17
	v_mov_b32_e32 v10, v18
	v_mov_b32_e32 v11, v19
	v_mov_b32_e32 v4, v20
	v_mov_b32_e32 v5, v21
	v_mov_b32_e32 v6, v22
	v_mov_b32_e32 v7, v23
	v_mov_b32_e32 v0, v24
	v_mov_b32_e32 v1, v25
	v_mov_b32_e32 v2, v26
	v_mov_b32_e32 v3, v27
	s_andn2_b64 exec, exec, s[4:5]
	s_cbranch_execz .LBB0_1324
.LBB0_1314:
	v_add_u32_e32 v32, s78, v32
	s_mov_b32 s0, 0x8000
	v_cmp_gt_i32_e32 vcc, s0, v32
	s_movk_i32 s0, 0x7fff
	v_cmp_lt_i32_e64 s[0:1], s0, v32
	v_mov_b32_e32 v12, v28
	v_mov_b32_e32 v13, v29
	v_mov_b32_e32 v14, v30
	v_mov_b32_e32 v15, v31
	v_mov_b32_e32 v16, v8
	v_mov_b32_e32 v17, v9
	v_mov_b32_e32 v18, v10
	v_mov_b32_e32 v19, v11
	v_mov_b32_e32 v20, v4
	v_mov_b32_e32 v21, v5
	v_mov_b32_e32 v22, v6
	v_mov_b32_e32 v23, v7
	v_mov_b32_e32 v24, v0
	v_mov_b32_e32 v25, v1
	v_mov_b32_e32 v26, v2
	v_mov_b32_e32 v27, v3
	s_and_saveexec_b64 s[2:3], vcc
	s_cbranch_execz .LBB0_1316
	v_lshl_add_u64 v[24:25], v[40:41], 0, v[192:193]
	global_load_dwordx4 v[12:15], v[24:25], off
	global_load_dwordx4 v[16:19], v[24:25], off offset:1024
	global_load_dwordx4 v[20:23], v[24:25], off offset:2048
	s_nop 0
	global_load_dwordx4 v[24:27], v[24:25], off offset:3072
	v_readfirstlane_b32 s99, v32
	s_add_i32 s99, s99, s78
	s_cmp_lt_i32 s99, 0x8000
	s_cbranch_scc0 .Lln2_pf0
	v_lshl_add_u64 v[98:99], v[40:41], 0, v[100:101]
	s_branch .Lln2_pf1
.Lln2_pf0:
	v_lshl_add_u64 v[98:99], v[40:41], 0, v[102:103]
.Lln2_pf1:
	global_load_dword v96, v[98:99], off
